# grid barrier: non-leader workgroups wait on the top-level generation word directly (one hop less)
# speedup vs baseline: 1.0067x; 1.0021x over previous
.LBB0_97:
	s_or_b64 exec, exec, s[8:9]
	v_cvt_f32_u32_e32 v5, v3
	s_waitcnt vmcnt(0)
	v_readfirstlane_b32 s2, v4
	v_sub_u32_e32 v4, 0, v3
	v_rcp_iflag_f32_e32 v5, v5
	v_add_u32_e32 v6, s2, v2
	v_mul_f32_e32 v5, 0x4f7ffffe, v5
	v_cvt_u32_f32_e32 v5, v5
	v_mul_lo_u32 v2, v4, v5
	v_mul_hi_u32 v2, v5, v2
	v_add_u32_e32 v2, v5, v2
	v_mul_hi_u32 v2, v6, v2
	v_mul_lo_u32 v4, v2, v3
	v_sub_u32_e32 v4, v6, v4
	v_add_u32_e32 v5, 1, v2
	v_cmp_ge_u32_e32 vcc, v4, v3
	s_nop 1
	v_cndmask_b32_e32 v2, v2, v5, vcc
	v_sub_u32_e32 v5, v4, v3
	v_cndmask_b32_e32 v4, v4, v5, vcc
	v_add_u32_e32 v5, 1, v2
	v_cmp_ge_u32_e32 vcc, v4, v3
	v_add_u32_e32 v4, 1, v6
	s_nop 0
	v_cndmask_b32_e32 v2, v2, v5, vcc
	v_mul_lo_u32 v5, v3, v2
	v_add_u32_e32 v3, v5, v3
	v_cmp_ne_u32_e32 vcc, v4, v3
	s_and_saveexec_b64 s[2:3], vcc
	s_xor_b64 s[6:7], exec, s[2:3]
	s_cbranch_execz .LBB0_111
	s_waitcnt lgkmcnt(0)
	v_mov_b32_e32 v1, 0x3500
	global_load_dword v1, v1, s[64:65] sc1
	s_add_u32 s10, s64, 0x3500
	s_addc_u32 s11, s65, 0
	s_waitcnt vmcnt(0)
	v_cmp_gt_u32_e32 vcc, 1, v1
	s_and_saveexec_b64 s[8:9], vcc
	s_cbranch_execz .LBB0_110
	s_mov_b32 s2, 1
	s_mov_b64 s[12:13], 0
	v_mov_b32_e32 v1, 0
	s_branch .LBB0_101

.LBB0_103:
	global_load_dword v3, v1, s[10:11] sc1
	s_add_i32 s2, s2, 1
	s_mov_b64 s[18:19], -1
	s_waitcnt vmcnt(0)
	v_cmp_le_u32_e32 vcc, 1, v3
	s_orn2_b64 s[16:17], vcc, exec
	s_branch .LBB0_100

.LBB0_197:
	s_or_b64 exec, exec, s[8:9]
	v_cvt_f32_u32_e32 v5, v3
	s_waitcnt vmcnt(0)
	v_readfirstlane_b32 s2, v4
	v_sub_u32_e32 v4, 0, v3
	v_rcp_iflag_f32_e32 v5, v5
	v_add_u32_e32 v6, s2, v2
	v_mul_f32_e32 v5, 0x4f7ffffe, v5
	v_cvt_u32_f32_e32 v5, v5
	v_mul_lo_u32 v2, v4, v5
	v_mul_hi_u32 v2, v5, v2
	v_add_u32_e32 v2, v5, v2
	v_mul_hi_u32 v2, v6, v2
	v_mul_lo_u32 v4, v2, v3
	v_sub_u32_e32 v4, v6, v4
	v_add_u32_e32 v5, 1, v2
	v_cmp_ge_u32_e32 vcc, v4, v3
	s_nop 1
	v_cndmask_b32_e32 v2, v2, v5, vcc
	v_sub_u32_e32 v5, v4, v3
	v_cndmask_b32_e32 v4, v4, v5, vcc
	v_add_u32_e32 v5, 1, v2
	v_cmp_ge_u32_e32 vcc, v4, v3
	v_add_u32_e32 v4, 1, v6
	s_nop 0
	v_cndmask_b32_e32 v2, v2, v5, vcc
	v_mul_lo_u32 v5, v3, v2
	v_add_u32_e32 v3, v5, v3
	v_cmp_ne_u32_e32 vcc, v4, v3
	s_and_saveexec_b64 s[2:3], vcc
	s_xor_b64 s[6:7], exec, s[2:3]
	s_cbranch_execz .LBB0_211
	s_waitcnt lgkmcnt(0)
	v_mov_b32_e32 v1, 0x3500
	global_load_dword v1, v1, s[64:65] sc1
	s_add_u32 s10, s64, 0x3500
	s_addc_u32 s11, s65, 0
	s_waitcnt vmcnt(0)
	v_cmp_gt_u32_e32 vcc, 2, v1
	s_and_saveexec_b64 s[8:9], vcc
	s_cbranch_execz .LBB0_210
	s_mov_b32 s2, 1
	s_mov_b64 s[12:13], 0
	v_mov_b32_e32 v1, 0
	s_branch .LBB0_201

.LBB0_203:
	global_load_dword v3, v1, s[10:11] sc1
	s_add_i32 s2, s2, 1
	s_mov_b64 s[18:19], -1
	s_waitcnt vmcnt(0)
	v_cmp_le_u32_e32 vcc, 2, v3
	s_orn2_b64 s[16:17], vcc, exec
	s_branch .LBB0_200

.LBB0_433:
	s_or_b64 exec, exec, s[8:9]
	v_cvt_f32_u32_e32 v5, v3
	s_waitcnt vmcnt(0)
	v_readfirstlane_b32 s2, v4
	v_sub_u32_e32 v4, 0, v3
	v_rcp_iflag_f32_e32 v5, v5
	v_add_u32_e32 v6, s2, v2
	v_mul_f32_e32 v5, 0x4f7ffffe, v5
	v_cvt_u32_f32_e32 v5, v5
	v_mul_lo_u32 v2, v4, v5
	v_mul_hi_u32 v2, v5, v2
	v_add_u32_e32 v2, v5, v2
	v_mul_hi_u32 v2, v6, v2
	v_mul_lo_u32 v4, v2, v3
	v_sub_u32_e32 v4, v6, v4
	v_add_u32_e32 v5, 1, v2
	v_cmp_ge_u32_e32 vcc, v4, v3
	s_nop 1
	v_cndmask_b32_e32 v2, v2, v5, vcc
	v_sub_u32_e32 v5, v4, v3
	v_cndmask_b32_e32 v4, v4, v5, vcc
	v_add_u32_e32 v5, 1, v2
	v_cmp_ge_u32_e32 vcc, v4, v3
	v_add_u32_e32 v4, 1, v6
	s_nop 0
	v_cndmask_b32_e32 v2, v2, v5, vcc
	v_mul_lo_u32 v5, v3, v2
	v_add_u32_e32 v3, v5, v3
	v_cmp_ne_u32_e32 vcc, v4, v3
	s_and_saveexec_b64 s[2:3], vcc
	s_xor_b64 s[6:7], exec, s[2:3]
	s_cbranch_execz .LBB0_447
	s_waitcnt lgkmcnt(0)
	v_mov_b32_e32 v1, 0x3500
	global_load_dword v1, v1, s[80:81] sc1
	s_add_u32 s10, s80, 0x3500
	s_addc_u32 s11, s81, 0
	s_waitcnt vmcnt(0)
	v_cmp_gt_u32_e32 vcc, 3, v1
	s_and_saveexec_b64 s[8:9], vcc
	s_cbranch_execz .LBB0_446
	s_mov_b32 s2, 1
	s_mov_b64 s[12:13], 0
	v_mov_b32_e32 v1, 0
	s_branch .LBB0_437

.LBB0_439:
	global_load_dword v3, v1, s[10:11] sc1
	s_add_i32 s2, s2, 1
	s_mov_b64 s[18:19], -1
	s_waitcnt vmcnt(0)
	v_cmp_le_u32_e32 vcc, 3, v3
	s_orn2_b64 s[16:17], vcc, exec
	s_branch .LBB0_436

.LBB0_702:
	s_or_b64 exec, exec, s[8:9]
	v_cvt_f32_u32_e32 v5, v3
	s_waitcnt vmcnt(0)
	v_readfirstlane_b32 s2, v4
	v_sub_u32_e32 v4, 0, v3
	v_rcp_iflag_f32_e32 v5, v5
	v_add_u32_e32 v6, s2, v2
	v_mul_f32_e32 v5, 0x4f7ffffe, v5
	v_cvt_u32_f32_e32 v5, v5
	v_mul_lo_u32 v2, v4, v5
	v_mul_hi_u32 v2, v5, v2
	v_add_u32_e32 v2, v5, v2
	v_mul_hi_u32 v2, v6, v2
	v_mul_lo_u32 v4, v2, v3
	v_sub_u32_e32 v4, v6, v4
	v_add_u32_e32 v5, 1, v2
	v_cmp_ge_u32_e32 vcc, v4, v3
	s_nop 1
	v_cndmask_b32_e32 v2, v2, v5, vcc
	v_sub_u32_e32 v5, v4, v3
	v_cndmask_b32_e32 v4, v4, v5, vcc
	v_add_u32_e32 v5, 1, v2
	v_cmp_ge_u32_e32 vcc, v4, v3
	v_add_u32_e32 v4, 1, v6
	s_nop 0
	v_cndmask_b32_e32 v2, v2, v5, vcc
	v_mul_lo_u32 v5, v3, v2
	v_add_u32_e32 v3, v5, v3
	v_cmp_ne_u32_e32 vcc, v4, v3
	s_and_saveexec_b64 s[2:3], vcc
	s_xor_b64 s[6:7], exec, s[2:3]
	s_cbranch_execz .LBB0_716
	s_waitcnt lgkmcnt(0)
	v_mov_b32_e32 v1, 0x3500
	global_load_dword v1, v1, s[80:81] sc1
	s_add_u32 s10, s80, 0x3500
	s_addc_u32 s11, s81, 0
	s_waitcnt vmcnt(0)
	v_cmp_gt_u32_e32 vcc, 4, v1
	s_and_saveexec_b64 s[8:9], vcc
	s_cbranch_execz .LBB0_715
	s_mov_b32 s2, 1
	s_mov_b64 s[12:13], 0
	v_mov_b32_e32 v1, 0
	s_branch .LBB0_706

.LBB0_708:
	global_load_dword v3, v1, s[10:11] sc1
	s_add_i32 s2, s2, 1
	s_mov_b64 s[18:19], -1
	s_waitcnt vmcnt(0)
	v_cmp_le_u32_e32 vcc, 4, v3
	s_orn2_b64 s[16:17], vcc, exec
	s_branch .LBB0_705

.LBB0_798:
	s_or_b64 exec, exec, s[8:9]
	v_cvt_f32_u32_e32 v5, v3
	s_waitcnt vmcnt(0)
	v_readfirstlane_b32 s2, v4
	v_sub_u32_e32 v4, 0, v3
	v_rcp_iflag_f32_e32 v5, v5
	v_add_u32_e32 v6, s2, v2
	v_mul_f32_e32 v5, 0x4f7ffffe, v5
	v_cvt_u32_f32_e32 v5, v5
	v_mul_lo_u32 v2, v4, v5
	v_mul_hi_u32 v2, v5, v2
	v_add_u32_e32 v2, v5, v2
	v_mul_hi_u32 v2, v6, v2
	v_mul_lo_u32 v4, v2, v3
	v_sub_u32_e32 v4, v6, v4
	v_add_u32_e32 v5, 1, v2
	v_cmp_ge_u32_e32 vcc, v4, v3
	s_nop 1
	v_cndmask_b32_e32 v2, v2, v5, vcc
	v_sub_u32_e32 v5, v4, v3
	v_cndmask_b32_e32 v4, v4, v5, vcc
	v_add_u32_e32 v5, 1, v2
	v_cmp_ge_u32_e32 vcc, v4, v3
	v_add_u32_e32 v4, 1, v6
	s_nop 0
	v_cndmask_b32_e32 v2, v2, v5, vcc
	v_mul_lo_u32 v5, v3, v2
	v_add_u32_e32 v3, v5, v3
	v_cmp_ne_u32_e32 vcc, v4, v3
	s_and_saveexec_b64 s[2:3], vcc
	s_xor_b64 s[6:7], exec, s[2:3]
	s_cbranch_execz .LBB0_812
	s_waitcnt lgkmcnt(0)
	v_mov_b32_e32 v1, 0x3500
	global_load_dword v1, v1, s[80:81] sc1
	s_add_u32 s10, s80, 0x3500
	s_addc_u32 s11, s81, 0
	s_waitcnt vmcnt(0)
	v_cmp_gt_u32_e32 vcc, 5, v1
	s_and_saveexec_b64 s[8:9], vcc
	s_cbranch_execz .LBB0_811
	s_mov_b32 s2, 1
	s_mov_b64 s[12:13], 0
	v_mov_b32_e32 v1, 0
	s_branch .LBB0_802

.LBB0_804:
	global_load_dword v3, v1, s[10:11] sc1
	s_add_i32 s2, s2, 1
	s_mov_b64 s[18:19], -1
	s_waitcnt vmcnt(0)
	v_cmp_le_u32_e32 vcc, 5, v3
	s_orn2_b64 s[16:17], vcc, exec
	s_branch .LBB0_801

.LBB0_868:
	s_or_b64 exec, exec, s[8:9]
	v_cvt_f32_u32_e32 v5, v3
	s_waitcnt vmcnt(0)
	v_readfirstlane_b32 s2, v4
	v_sub_u32_e32 v4, 0, v3
	v_rcp_iflag_f32_e32 v5, v5
	v_add_u32_e32 v6, s2, v2
	v_mul_f32_e32 v5, 0x4f7ffffe, v5
	v_cvt_u32_f32_e32 v5, v5
	v_mul_lo_u32 v2, v4, v5
	v_mul_hi_u32 v2, v5, v2
	v_add_u32_e32 v2, v5, v2
	v_mul_hi_u32 v2, v6, v2
	v_mul_lo_u32 v4, v2, v3
	v_sub_u32_e32 v4, v6, v4
	v_add_u32_e32 v5, 1, v2
	v_cmp_ge_u32_e32 vcc, v4, v3
	s_nop 1
	v_cndmask_b32_e32 v2, v2, v5, vcc
	v_sub_u32_e32 v5, v4, v3
	v_cndmask_b32_e32 v4, v4, v5, vcc
	v_add_u32_e32 v5, 1, v2
	v_cmp_ge_u32_e32 vcc, v4, v3
	v_add_u32_e32 v4, 1, v6
	s_nop 0
	v_cndmask_b32_e32 v2, v2, v5, vcc
	v_mul_lo_u32 v5, v3, v2
	v_add_u32_e32 v3, v5, v3
	v_cmp_ne_u32_e32 vcc, v4, v3
	s_and_saveexec_b64 s[2:3], vcc
	s_xor_b64 s[6:7], exec, s[2:3]
	s_cbranch_execz .LBB0_882
	s_waitcnt lgkmcnt(0)
	v_mov_b32_e32 v1, 0x3500
	global_load_dword v1, v1, s[80:81] sc1
	s_add_u32 s10, s80, 0x3500
	s_addc_u32 s11, s81, 0
	s_waitcnt vmcnt(0)
	v_cmp_gt_u32_e32 vcc, 6, v1
	s_and_saveexec_b64 s[8:9], vcc
	s_cbranch_execz .LBB0_881
	s_mov_b32 s2, 1
	s_mov_b64 s[12:13], 0
	v_mov_b32_e32 v1, 0
	s_branch .LBB0_872

.LBB0_874:
	global_load_dword v3, v1, s[10:11] sc1
	s_add_i32 s2, s2, 1
	s_mov_b64 s[18:19], -1
	s_waitcnt vmcnt(0)
	v_cmp_le_u32_e32 vcc, 6, v3
	s_orn2_b64 s[16:17], vcc, exec
	s_branch .LBB0_871

.LBB0_1059:
	s_or_b64 exec, exec, s[8:9]
	v_cvt_f32_u32_e32 v5, v3
	s_waitcnt vmcnt(0)
	v_readfirstlane_b32 s2, v4
	v_sub_u32_e32 v4, 0, v3
	v_rcp_iflag_f32_e32 v5, v5
	v_add_u32_e32 v6, s2, v2
	v_mul_f32_e32 v5, 0x4f7ffffe, v5
	v_cvt_u32_f32_e32 v5, v5
	v_mul_lo_u32 v2, v4, v5
	v_mul_hi_u32 v2, v5, v2
	v_add_u32_e32 v2, v5, v2
	v_mul_hi_u32 v2, v6, v2
	v_mul_lo_u32 v4, v2, v3
	v_sub_u32_e32 v4, v6, v4
	v_add_u32_e32 v5, 1, v2
	v_cmp_ge_u32_e32 vcc, v4, v3
	s_nop 1
	v_cndmask_b32_e32 v2, v2, v5, vcc
	v_sub_u32_e32 v5, v4, v3
	v_cndmask_b32_e32 v4, v4, v5, vcc
	v_add_u32_e32 v5, 1, v2
	v_cmp_ge_u32_e32 vcc, v4, v3
	v_add_u32_e32 v4, 1, v6
	s_nop 0
	v_cndmask_b32_e32 v2, v2, v5, vcc
	v_mul_lo_u32 v5, v3, v2
	v_add_u32_e32 v3, v5, v3
	v_cmp_ne_u32_e32 vcc, v4, v3
	s_and_saveexec_b64 s[2:3], vcc
	s_xor_b64 s[6:7], exec, s[2:3]
	s_cbranch_execz .LBB0_1073
	s_waitcnt lgkmcnt(0)
	v_mov_b32_e32 v1, 0x3500
	global_load_dword v1, v1, s[80:81] sc1
	s_add_u32 s10, s80, 0x3500
	s_addc_u32 s11, s81, 0
	s_waitcnt vmcnt(0)
	v_cmp_gt_u32_e32 vcc, 7, v1
	s_and_saveexec_b64 s[8:9], vcc
	s_cbranch_execz .LBB0_1072
	s_mov_b32 s2, 1
	s_mov_b64 s[12:13], 0
	v_mov_b32_e32 v1, 0
	s_branch .LBB0_1063

.LBB0_1065:
	global_load_dword v3, v1, s[10:11] sc1
	s_add_i32 s2, s2, 1
	s_mov_b64 s[18:19], -1
	s_waitcnt vmcnt(0)
	v_cmp_le_u32_e32 vcc, 7, v3
	s_orn2_b64 s[16:17], vcc, exec
	s_branch .LBB0_1062

.LBB0_1155:
	s_or_b64 exec, exec, s[8:9]
	v_cvt_f32_u32_e32 v5, v3
	s_waitcnt vmcnt(0)
	v_readfirstlane_b32 s2, v4
	v_sub_u32_e32 v4, 0, v3
	v_rcp_iflag_f32_e32 v5, v5
	v_add_u32_e32 v6, s2, v2
	v_mul_f32_e32 v5, 0x4f7ffffe, v5
	v_cvt_u32_f32_e32 v5, v5
	v_mul_lo_u32 v2, v4, v5
	v_mul_hi_u32 v2, v5, v2
	v_add_u32_e32 v2, v5, v2
	v_mul_hi_u32 v2, v6, v2
	v_mul_lo_u32 v4, v2, v3
	v_sub_u32_e32 v4, v6, v4
	v_add_u32_e32 v5, 1, v2
	v_cmp_ge_u32_e32 vcc, v4, v3
	s_nop 1
	v_cndmask_b32_e32 v2, v2, v5, vcc
	v_sub_u32_e32 v5, v4, v3
	v_cndmask_b32_e32 v4, v4, v5, vcc
	v_add_u32_e32 v5, 1, v2
	v_cmp_ge_u32_e32 vcc, v4, v3
	v_add_u32_e32 v4, 1, v6
	s_nop 0
	v_cndmask_b32_e32 v2, v2, v5, vcc
	v_mul_lo_u32 v5, v3, v2
	v_add_u32_e32 v3, v5, v3
	v_cmp_ne_u32_e32 vcc, v4, v3
	s_and_saveexec_b64 s[2:3], vcc
	s_xor_b64 s[6:7], exec, s[2:3]
	s_cbranch_execz .LBB0_1169
	s_waitcnt lgkmcnt(0)
	v_mov_b32_e32 v1, 0x3500
	global_load_dword v1, v1, s[80:81] sc1
	s_add_u32 s10, s80, 0x3500
	s_addc_u32 s11, s81, 0
	s_waitcnt vmcnt(0)
	v_cmp_gt_u32_e32 vcc, 8, v1
	s_and_saveexec_b64 s[8:9], vcc
	s_cbranch_execz .LBB0_1168
	s_mov_b32 s2, 1
	s_mov_b64 s[12:13], 0
	v_mov_b32_e32 v1, 0
	s_branch .LBB0_1159

.LBB0_1161:
	global_load_dword v3, v1, s[10:11] sc1
	s_add_i32 s2, s2, 1
	s_mov_b64 s[18:19], -1
	s_waitcnt vmcnt(0)
	v_cmp_le_u32_e32 vcc, 8, v3
	s_orn2_b64 s[16:17], vcc, exec
	s_branch .LBB0_1158

.LBB0_1225:
	s_or_b64 exec, exec, s[8:9]
	v_cvt_f32_u32_e32 v5, v3
	s_waitcnt vmcnt(0)
	v_readfirstlane_b32 s2, v4
	v_sub_u32_e32 v4, 0, v3
	v_rcp_iflag_f32_e32 v5, v5
	v_add_u32_e32 v6, s2, v2
	v_mul_f32_e32 v5, 0x4f7ffffe, v5
	v_cvt_u32_f32_e32 v5, v5
	v_mul_lo_u32 v2, v4, v5
	v_mul_hi_u32 v2, v5, v2
	v_add_u32_e32 v2, v5, v2
	v_mul_hi_u32 v2, v6, v2
	v_mul_lo_u32 v4, v2, v3
	v_sub_u32_e32 v4, v6, v4
	v_add_u32_e32 v5, 1, v2
	v_cmp_ge_u32_e32 vcc, v4, v3
	s_nop 1
	v_cndmask_b32_e32 v2, v2, v5, vcc
	v_sub_u32_e32 v5, v4, v3
	v_cndmask_b32_e32 v4, v4, v5, vcc
	v_add_u32_e32 v5, 1, v2
	v_cmp_ge_u32_e32 vcc, v4, v3
	v_add_u32_e32 v4, 1, v6
	s_nop 0
	v_cndmask_b32_e32 v2, v2, v5, vcc
	v_mul_lo_u32 v5, v3, v2
	v_add_u32_e32 v3, v5, v3
	v_cmp_ne_u32_e32 vcc, v4, v3
	s_and_saveexec_b64 s[2:3], vcc
	s_xor_b64 s[6:7], exec, s[2:3]
	s_cbranch_execz .LBB0_1239
	s_waitcnt lgkmcnt(0)
	v_mov_b32_e32 v1, 0x3500
	global_load_dword v1, v1, s[80:81] sc1
	s_add_u32 s10, s80, 0x3500
	s_addc_u32 s11, s81, 0
	s_waitcnt vmcnt(0)
	v_cmp_gt_u32_e32 vcc, 9, v1
	s_and_saveexec_b64 s[8:9], vcc
	s_cbranch_execz .LBB0_1238
	s_mov_b32 s2, 1
	s_mov_b64 s[12:13], 0
	v_mov_b32_e32 v1, 0
	s_branch .LBB0_1229

.LBB0_1231:
	global_load_dword v3, v1, s[10:11] sc1
	s_add_i32 s2, s2, 1
	s_mov_b64 s[18:19], -1
	s_waitcnt vmcnt(0)
	v_cmp_le_u32_e32 vcc, 9, v3
	s_orn2_b64 s[16:17], vcc, exec
	s_branch .LBB0_1228

.LBB0_1314:
	s_or_b64 exec, exec, s[8:9]
	v_cvt_f32_u32_e32 v5, v3
	s_waitcnt vmcnt(0)
	v_readfirstlane_b32 s2, v4
	v_sub_u32_e32 v4, 0, v3
	v_rcp_iflag_f32_e32 v5, v5
	v_add_u32_e32 v6, s2, v2
	v_mul_f32_e32 v5, 0x4f7ffffe, v5
	v_cvt_u32_f32_e32 v5, v5
	v_mul_lo_u32 v2, v4, v5
	v_mul_hi_u32 v2, v5, v2
	v_add_u32_e32 v2, v5, v2
	v_mul_hi_u32 v2, v6, v2
	v_mul_lo_u32 v4, v2, v3
	v_sub_u32_e32 v4, v6, v4
	v_add_u32_e32 v5, 1, v2
	v_cmp_ge_u32_e32 vcc, v4, v3
	s_nop 1
	v_cndmask_b32_e32 v2, v2, v5, vcc
	v_sub_u32_e32 v5, v4, v3
	v_cndmask_b32_e32 v4, v4, v5, vcc
	v_add_u32_e32 v5, 1, v2
	v_cmp_ge_u32_e32 vcc, v4, v3
	v_add_u32_e32 v4, 1, v6
	s_nop 0
	v_cndmask_b32_e32 v2, v2, v5, vcc
	v_mul_lo_u32 v5, v3, v2
	v_add_u32_e32 v3, v5, v3
	v_cmp_ne_u32_e32 vcc, v4, v3
	s_and_saveexec_b64 s[2:3], vcc
	s_xor_b64 s[6:7], exec, s[2:3]
	s_cbranch_execz .LBB0_1328
	s_waitcnt lgkmcnt(0)
	v_mov_b32_e32 v1, 0x3500
	global_load_dword v1, v1, s[80:81] sc1
	s_add_u32 s10, s80, 0x3500
	s_addc_u32 s11, s81, 0
	s_waitcnt vmcnt(0)
	v_cmp_gt_u32_e32 vcc, 10, v1
	s_and_saveexec_b64 s[8:9], vcc
	s_cbranch_execz .LBB0_1327
	s_mov_b32 s2, 1
	s_mov_b64 s[12:13], 0
	v_mov_b32_e32 v1, 0
	s_branch .LBB0_1318

.LBB0_1320:
	global_load_dword v3, v1, s[10:11] sc1
	s_add_i32 s2, s2, 1
	s_mov_b64 s[18:19], -1
	s_waitcnt vmcnt(0)
	v_cmp_le_u32_e32 vcc, 10, v3
	s_orn2_b64 s[16:17], vcc, exec
	s_branch .LBB0_1317

.LBB0_1592:
	s_or_b64 exec, exec, s[8:9]
	v_cvt_f32_u32_e32 v5, v3
	s_waitcnt vmcnt(0)
	v_readfirstlane_b32 s2, v4
	v_sub_u32_e32 v4, 0, v3
	v_rcp_iflag_f32_e32 v5, v5
	v_add_u32_e32 v6, s2, v2
	v_mul_f32_e32 v5, 0x4f7ffffe, v5
	v_cvt_u32_f32_e32 v5, v5
	v_mul_lo_u32 v2, v4, v5
	v_mul_hi_u32 v2, v5, v2
	v_add_u32_e32 v2, v5, v2
	v_mul_hi_u32 v2, v6, v2
	v_mul_lo_u32 v4, v2, v3
	v_sub_u32_e32 v4, v6, v4
	v_add_u32_e32 v5, 1, v2
	v_cmp_ge_u32_e32 vcc, v4, v3
	s_nop 1
	v_cndmask_b32_e32 v2, v2, v5, vcc
	v_sub_u32_e32 v5, v4, v3
	v_cndmask_b32_e32 v4, v4, v5, vcc
	v_add_u32_e32 v5, 1, v2
	v_cmp_ge_u32_e32 vcc, v4, v3
	v_add_u32_e32 v4, 1, v6
	s_nop 0
	v_cndmask_b32_e32 v2, v2, v5, vcc
	v_mul_lo_u32 v5, v3, v2
	v_add_u32_e32 v3, v5, v3
	v_cmp_ne_u32_e32 vcc, v4, v3
	s_and_saveexec_b64 s[2:3], vcc
	s_xor_b64 s[6:7], exec, s[2:3]
	s_cbranch_execz .LBB0_1606
	s_waitcnt lgkmcnt(0)
	v_mov_b32_e32 v1, 0x3500
	global_load_dword v1, v1, s[80:81] sc1
	s_add_u32 s10, s80, 0x3500
	s_addc_u32 s11, s81, 0
	s_waitcnt vmcnt(0)
	v_cmp_gt_u32_e32 vcc, 11, v1
	s_and_saveexec_b64 s[8:9], vcc
	s_cbranch_execz .LBB0_1605
	s_mov_b32 s2, 1
	s_mov_b64 s[12:13], 0
	v_mov_b32_e32 v1, 0
	s_branch .LBB0_1596

.LBB0_1598:
	global_load_dword v3, v1, s[10:11] sc1
	s_add_i32 s2, s2, 1
	s_mov_b64 s[18:19], -1
	s_waitcnt vmcnt(0)
	v_cmp_le_u32_e32 vcc, 11, v3
	s_orn2_b64 s[16:17], vcc, exec
	s_branch .LBB0_1595

.LBB0_1672:
	s_or_b64 exec, exec, s[8:9]
	v_cvt_f32_u32_e32 v5, v3
	s_waitcnt vmcnt(0)
	v_readfirstlane_b32 s2, v4
	v_sub_u32_e32 v4, 0, v3
	v_rcp_iflag_f32_e32 v5, v5
	v_add_u32_e32 v6, s2, v2
	v_mul_f32_e32 v5, 0x4f7ffffe, v5
	v_cvt_u32_f32_e32 v5, v5
	v_mul_lo_u32 v2, v4, v5
	v_mul_hi_u32 v2, v5, v2
	v_add_u32_e32 v2, v5, v2
	v_mul_hi_u32 v2, v6, v2
	v_mul_lo_u32 v4, v2, v3
	v_sub_u32_e32 v4, v6, v4
	v_add_u32_e32 v5, 1, v2
	v_cmp_ge_u32_e32 vcc, v4, v3
	s_nop 1
	v_cndmask_b32_e32 v2, v2, v5, vcc
	v_sub_u32_e32 v5, v4, v3
	v_cndmask_b32_e32 v4, v4, v5, vcc
	v_add_u32_e32 v5, 1, v2
	v_cmp_ge_u32_e32 vcc, v4, v3
	v_add_u32_e32 v4, 1, v6
	s_nop 0
	v_cndmask_b32_e32 v2, v2, v5, vcc
	v_mul_lo_u32 v5, v3, v2
	v_add_u32_e32 v3, v5, v3
	v_cmp_ne_u32_e32 vcc, v4, v3
	s_and_saveexec_b64 s[2:3], vcc
	s_xor_b64 s[6:7], exec, s[2:3]
	s_cbranch_execz .LBB0_1686
	s_waitcnt lgkmcnt(0)
	v_mov_b32_e32 v1, 0x3500
	global_load_dword v1, v1, s[80:81] sc1
	s_add_u32 s10, s80, 0x3500
	s_addc_u32 s11, s81, 0
	s_waitcnt vmcnt(0)
	v_cmp_gt_u32_e32 vcc, 12, v1
	s_and_saveexec_b64 s[8:9], vcc
	s_cbranch_execz .LBB0_1685
	s_mov_b32 s2, 1
	s_mov_b64 s[12:13], 0
	v_mov_b32_e32 v1, 0
	s_branch .LBB0_1676

.LBB0_1678:
	global_load_dword v3, v1, s[10:11] sc1
	s_add_i32 s2, s2, 1
	s_mov_b64 s[18:19], -1
	s_waitcnt vmcnt(0)
	v_cmp_le_u32_e32 vcc, 12, v3
	s_orn2_b64 s[16:17], vcc, exec
	s_branch .LBB0_1675

.LBB0_1742:
	s_or_b64 exec, exec, s[8:9]
	v_cvt_f32_u32_e32 v5, v3
	s_waitcnt vmcnt(0)
	v_readfirstlane_b32 s2, v4
	v_sub_u32_e32 v4, 0, v3
	v_rcp_iflag_f32_e32 v5, v5
	v_add_u32_e32 v6, s2, v2
	v_mul_f32_e32 v5, 0x4f7ffffe, v5
	v_cvt_u32_f32_e32 v5, v5
	v_mul_lo_u32 v2, v4, v5
	v_mul_hi_u32 v2, v5, v2
	v_add_u32_e32 v2, v5, v2
	v_mul_hi_u32 v2, v6, v2
	v_mul_lo_u32 v4, v2, v3
	v_sub_u32_e32 v4, v6, v4
	v_add_u32_e32 v5, 1, v2
	v_cmp_ge_u32_e32 vcc, v4, v3
	s_nop 1
	v_cndmask_b32_e32 v2, v2, v5, vcc
	v_sub_u32_e32 v5, v4, v3
	v_cndmask_b32_e32 v4, v4, v5, vcc
	v_add_u32_e32 v5, 1, v2
	v_cmp_ge_u32_e32 vcc, v4, v3
	v_add_u32_e32 v4, 1, v6
	s_nop 0
	v_cndmask_b32_e32 v2, v2, v5, vcc
	v_mul_lo_u32 v5, v3, v2
	v_add_u32_e32 v3, v5, v3
	v_cmp_ne_u32_e32 vcc, v4, v3
	s_and_saveexec_b64 s[2:3], vcc
	s_xor_b64 s[6:7], exec, s[2:3]
	s_cbranch_execz .LBB0_1756
	s_waitcnt lgkmcnt(0)
	v_mov_b32_e32 v1, 0x3500
	global_load_dword v1, v1, s[80:81] sc1
	s_add_u32 s10, s80, 0x3500
	s_addc_u32 s11, s81, 0
	s_waitcnt vmcnt(0)
	v_cmp_gt_u32_e32 vcc, 13, v1
	s_and_saveexec_b64 s[8:9], vcc
	s_cbranch_execz .LBB0_1755
	s_mov_b32 s2, 1
	s_mov_b64 s[12:13], 0
	v_mov_b32_e32 v1, 0
	s_branch .LBB0_1746

.LBB0_1748:
	global_load_dword v3, v1, s[10:11] sc1
	s_add_i32 s2, s2, 1
	s_mov_b64 s[18:19], -1
	s_waitcnt vmcnt(0)
	v_cmp_le_u32_e32 vcc, 13, v3
	s_orn2_b64 s[16:17], vcc, exec
	s_branch .LBB0_1745

.LBB0_1848:
	s_or_b64 exec, exec, s[8:9]
	v_cvt_f32_u32_e32 v5, v3
	s_waitcnt vmcnt(0)
	v_readfirstlane_b32 s2, v4
	v_sub_u32_e32 v4, 0, v3
	v_rcp_iflag_f32_e32 v5, v5
	v_add_u32_e32 v6, s2, v2
	v_mul_f32_e32 v5, 0x4f7ffffe, v5
	v_cvt_u32_f32_e32 v5, v5
	v_mul_lo_u32 v2, v4, v5
	v_mul_hi_u32 v2, v5, v2
	v_add_u32_e32 v2, v5, v2
	v_mul_hi_u32 v2, v6, v2
	v_mul_lo_u32 v4, v2, v3
	v_sub_u32_e32 v4, v6, v4
	v_add_u32_e32 v5, 1, v2
	v_cmp_ge_u32_e32 vcc, v4, v3
	s_nop 1
	v_cndmask_b32_e32 v2, v2, v5, vcc
	v_sub_u32_e32 v5, v4, v3
	v_cndmask_b32_e32 v4, v4, v5, vcc
	v_add_u32_e32 v5, 1, v2
	v_cmp_ge_u32_e32 vcc, v4, v3
	v_add_u32_e32 v4, 1, v6
	s_nop 0
	v_cndmask_b32_e32 v2, v2, v5, vcc
	v_mul_lo_u32 v5, v3, v2
	v_add_u32_e32 v3, v5, v3
	v_cmp_ne_u32_e32 vcc, v4, v3
	s_and_saveexec_b64 s[2:3], vcc
	s_xor_b64 s[6:7], exec, s[2:3]
	s_cbranch_execz .LBB0_1862
	s_waitcnt lgkmcnt(0)
	v_mov_b32_e32 v1, 0x3500
	global_load_dword v1, v1, s[80:81] sc1
	s_add_u32 s10, s80, 0x3500
	s_addc_u32 s11, s81, 0
	s_waitcnt vmcnt(0)
	v_cmp_gt_u32_e32 vcc, 14, v1
	s_and_saveexec_b64 s[8:9], vcc
	s_cbranch_execz .LBB0_1861
	s_mov_b32 s2, 1
	s_mov_b64 s[12:13], 0
	v_mov_b32_e32 v1, 0
	s_branch .LBB0_1852

.LBB0_1854:
	global_load_dword v3, v1, s[10:11] sc1
	s_add_i32 s2, s2, 1
	s_mov_b64 s[18:19], -1
	s_waitcnt vmcnt(0)
	v_cmp_le_u32_e32 vcc, 14, v3
	s_orn2_b64 s[16:17], vcc, exec
	s_branch .LBB0_1851

.LBB0_1941:
	s_or_b64 exec, exec, s[8:9]
	v_cvt_f32_u32_e32 v5, v3
	s_waitcnt vmcnt(0)
	v_readfirstlane_b32 s2, v4
	v_sub_u32_e32 v4, 0, v3
	v_rcp_iflag_f32_e32 v5, v5
	v_add_u32_e32 v6, s2, v2
	v_mul_f32_e32 v5, 0x4f7ffffe, v5
	v_cvt_u32_f32_e32 v5, v5
	v_mul_lo_u32 v2, v4, v5
	v_mul_hi_u32 v2, v5, v2
	v_add_u32_e32 v2, v5, v2
	v_mul_hi_u32 v2, v6, v2
	v_mul_lo_u32 v4, v2, v3
	v_sub_u32_e32 v4, v6, v4
	v_add_u32_e32 v5, 1, v2
	v_cmp_ge_u32_e32 vcc, v4, v3
	s_nop 1
	v_cndmask_b32_e32 v2, v2, v5, vcc
	v_sub_u32_e32 v5, v4, v3
	v_cndmask_b32_e32 v4, v4, v5, vcc
	v_add_u32_e32 v5, 1, v2
	v_cmp_ge_u32_e32 vcc, v4, v3
	v_add_u32_e32 v4, 1, v6
	s_nop 0
	v_cndmask_b32_e32 v2, v2, v5, vcc
	v_mul_lo_u32 v5, v3, v2
	v_add_u32_e32 v3, v5, v3
	v_cmp_ne_u32_e32 vcc, v4, v3
	s_and_saveexec_b64 s[2:3], vcc
	s_xor_b64 s[6:7], exec, s[2:3]
	s_cbranch_execz .LBB0_1955
	s_waitcnt lgkmcnt(0)
	v_mov_b32_e32 v1, 0x3500
	global_load_dword v1, v1, s[80:81] sc1
	s_add_u32 s10, s80, 0x3500
	s_addc_u32 s11, s81, 0
	s_waitcnt vmcnt(0)
	v_cmp_gt_u32_e32 vcc, 15, v1
	s_and_saveexec_b64 s[8:9], vcc
	s_cbranch_execz .LBB0_1954
	s_mov_b32 s2, 1
	s_mov_b64 s[12:13], 0
	v_mov_b32_e32 v1, 0
	s_branch .LBB0_1945

.LBB0_1947:
	global_load_dword v3, v1, s[10:11] sc1
	s_add_i32 s2, s2, 1
	s_mov_b64 s[18:19], -1
	s_waitcnt vmcnt(0)
	v_cmp_le_u32_e32 vcc, 15, v3
	s_orn2_b64 s[16:17], vcc, exec
	s_branch .LBB0_1944
